# same as previous best with the LRU pass-2 LDS reads kept at or below 15 outstanding
# speedup vs baseline: 1.0157x; 1.0022x over previous
; #define LAS __attribute__((address_space(3)))
; __device__ __forceinline__ float bf2f(bf16_t b) { return __uint_as_float((unsigned)b << 16); }
; __device__ __forceinline__ unsigned cvt_pk_bf16(float lo, float hi) { unsigned r; asm volatile("v_cvt_pk_bf16_f32 %0, %1, %2" : "=v"(r) : "v"(lo), "v"(hi)); return r; }
; __device__ __forceinline__ float gelu_tanh(float x) { const float y = 0.7978845608028654f * (x + 0.044715f * x * x * x); const float e = __expf(2.f * y); return 0.5f * x * (2.f - 2.f * __builtin_amdgcn_rcpf(1.f + e)); }
; __device__ __forceinline__ void lru_chain(unsigned char* ws_, const float* const* in_, int l_, LAS unsigned char* lds, int tid, int bid, int G) {
;     ...
;             for (int i = 0; i < 16; i += 2) { hh = av[i] * hh + bv[i]; const float h0 = hh; hh = av[i + 1] * hh + bv[i + 1]; const int tl = 16 * w + i;
;                 const float g0 = gelu_tanh(bf2f(*(const LAS bf16_t*)(GT + tl * 144 + lane * 2))), g1 = gelu_tanh(bf2f(*(const LAS bf16_t*)(GT + (tl + 1) * 144 + lane * 2)));
;                 const unsigned pk = cvt_pk_bf16(g0 * h0, g1 * hh);
;                 *(LAS bf16_t*)(OT + tl * 144 + lane * 2) = (bf16_t)(pk & 0xffffu); *(LAS bf16_t*)(OT + (tl + 1) * 144 + lane * 2) = (bf16_t)(pk >> 16); }
.LBB0_203:
	s_waitcnt lgkmcnt(0)
	ds_read_u16 v216, v204
	ds_read_u16 v217, v204 offset:144
	ds_read_u16 v218, v204 offset:288
	ds_read_u16 v219, v204 offset:432
	ds_read_u16 v220, v204 offset:576
	ds_read_u16 v221, v204 offset:720
	ds_read_u16 v222, v204 offset:864
	ds_read_u16 v223, v204 offset:1008
	ds_read_u16 v224, v204 offset:1152
	ds_read_u16 v225, v204 offset:1296
	ds_read_u16 v226, v204 offset:1440
	ds_read_u16 v227, v204 offset:1584
	ds_read_u16 v228, v204 offset:1728
	ds_read_u16 v229, v204 offset:1872
	ds_read_u16 v230, v204 offset:2016
	s_and_b64 vcc, exec, s[50:51]
	s_waitcnt lgkmcnt(14)
	ds_read_u16 v231, v204 offset:2160
	s_mov_b32 s16, 0x3d372713
	s_mov_b32 s18, 0x3f4c422a
	s_mov_b32 s20, 0x3fb8aa3b
	s_mov_b32 s22, 0.5
	s_mov_b32 s6, 1.0
	s_mov_b32 s10, -2.0
	s_mov_b32 s100, 2.0
	s_waitcnt lgkmcnt(15)
	v_lshlrev_b32_e32 v216, 16, v216
	s_waitcnt lgkmcnt(14)
	v_lshlrev_b32_e32 v217, 16, v217
	s_waitcnt lgkmcnt(13)
	v_lshlrev_b32_e32 v218, 16, v218
	s_waitcnt lgkmcnt(12)
	v_lshlrev_b32_e32 v219, 16, v219
	s_waitcnt lgkmcnt(11)
	v_lshlrev_b32_e32 v220, 16, v220
	s_waitcnt lgkmcnt(10)
	v_lshlrev_b32_e32 v221, 16, v221
	s_waitcnt lgkmcnt(9)
	v_lshlrev_b32_e32 v222, 16, v222
	s_waitcnt lgkmcnt(8)
	v_lshlrev_b32_e32 v223, 16, v223
	s_waitcnt lgkmcnt(7)
	v_lshlrev_b32_e32 v224, 16, v224
	s_waitcnt lgkmcnt(6)
	v_lshlrev_b32_e32 v225, 16, v225
	s_waitcnt lgkmcnt(5)
	v_lshlrev_b32_e32 v226, 16, v226
	s_waitcnt lgkmcnt(4)
	v_lshlrev_b32_e32 v227, 16, v227
	s_waitcnt lgkmcnt(3)
	v_lshlrev_b32_e32 v228, 16, v228
	s_waitcnt lgkmcnt(2)
	v_lshlrev_b32_e32 v229, 16, v229
	s_waitcnt lgkmcnt(1)
	v_lshlrev_b32_e32 v230, 16, v230
	s_waitcnt lgkmcnt(0)
	v_lshlrev_b32_e32 v231, 16, v231
	v_fma_f32 v96, v100, v1, v96
	v_fmac_f32_e32 v97, v101, v96
	v_pk_mul_f32 v[234:235], v[216:217], s[16:17] op_sel_hi:[1,0]
	v_pk_mul_f32 v[236:237], v[218:219], s[16:17] op_sel_hi:[1,0]
	v_pk_mul_f32 v[238:239], v[220:221], s[16:17] op_sel_hi:[1,0]
	v_pk_mul_f32 v[240:241], v[222:223], s[16:17] op_sel_hi:[1,0]
	v_pk_mul_f32 v[242:243], v[224:225], s[16:17] op_sel_hi:[1,0]
	v_pk_mul_f32 v[244:245], v[226:227], s[16:17] op_sel_hi:[1,0]
	v_pk_mul_f32 v[246:247], v[228:229], s[16:17] op_sel_hi:[1,0]
	v_pk_mul_f32 v[248:249], v[230:231], s[16:17] op_sel_hi:[1,0]
	v_fmac_f32_e32 v92, v98, v97
	v_fmac_f32_e32 v93, v99, v92
	v_pk_mul_f32 v[234:235], v[234:235], v[216:217]
	v_pk_mul_f32 v[236:237], v[236:237], v[218:219]
	v_pk_mul_f32 v[238:239], v[238:239], v[220:221]
	v_pk_mul_f32 v[240:241], v[240:241], v[222:223]
	v_pk_mul_f32 v[242:243], v[242:243], v[224:225]
	v_pk_mul_f32 v[244:245], v[244:245], v[226:227]
	v_pk_mul_f32 v[246:247], v[246:247], v[228:229]
	v_pk_mul_f32 v[248:249], v[248:249], v[230:231]
	v_fmac_f32_e32 v88, v94, v93
	v_fmac_f32_e32 v89, v95, v88
	v_pk_fma_f32 v[234:235], v[234:235], v[216:217], v[216:217]
	v_pk_fma_f32 v[236:237], v[236:237], v[218:219], v[218:219]
	v_pk_fma_f32 v[238:239], v[238:239], v[220:221], v[220:221]
	v_pk_fma_f32 v[240:241], v[240:241], v[222:223], v[222:223]
	v_pk_fma_f32 v[242:243], v[242:243], v[224:225], v[224:225]
	v_pk_fma_f32 v[244:245], v[244:245], v[226:227], v[226:227]
	v_pk_fma_f32 v[246:247], v[246:247], v[228:229], v[228:229]
	v_pk_fma_f32 v[248:249], v[248:249], v[230:231], v[230:231]
	v_fmac_f32_e32 v84, v90, v89
	v_fmac_f32_e32 v85, v91, v84
	v_pk_mul_f32 v[234:235], v[234:235], s[18:19] op_sel_hi:[1,0]
	v_pk_mul_f32 v[236:237], v[236:237], s[18:19] op_sel_hi:[1,0]
	v_pk_mul_f32 v[238:239], v[238:239], s[18:19] op_sel_hi:[1,0]
	v_pk_mul_f32 v[240:241], v[240:241], s[18:19] op_sel_hi:[1,0]
	v_pk_mul_f32 v[242:243], v[242:243], s[18:19] op_sel_hi:[1,0]
	v_pk_mul_f32 v[244:245], v[244:245], s[18:19] op_sel_hi:[1,0]
	v_pk_mul_f32 v[246:247], v[246:247], s[18:19] op_sel_hi:[1,0]
	v_pk_mul_f32 v[248:249], v[248:249], s[18:19] op_sel_hi:[1,0]
	v_fmac_f32_e32 v80, v86, v85
	v_fmac_f32_e32 v81, v87, v80
	v_pk_add_f32 v[234:235], v[234:235], v[234:235]
	v_pk_add_f32 v[236:237], v[236:237], v[236:237]
	v_pk_add_f32 v[238:239], v[238:239], v[238:239]
	v_pk_add_f32 v[240:241], v[240:241], v[240:241]
	v_pk_add_f32 v[242:243], v[242:243], v[242:243]
	v_pk_add_f32 v[244:245], v[244:245], v[244:245]
	v_pk_add_f32 v[246:247], v[246:247], v[246:247]
	v_pk_add_f32 v[248:249], v[248:249], v[248:249]
	v_fmac_f32_e32 v76, v82, v81
	v_fmac_f32_e32 v77, v83, v76
	v_pk_mul_f32 v[234:235], v[234:235], s[20:21] op_sel_hi:[1,0]
	v_pk_mul_f32 v[236:237], v[236:237], s[20:21] op_sel_hi:[1,0]
	v_pk_mul_f32 v[238:239], v[238:239], s[20:21] op_sel_hi:[1,0]
	v_pk_mul_f32 v[240:241], v[240:241], s[20:21] op_sel_hi:[1,0]
; #define LAS __attribute__((address_space(3)))
; __device__ __forceinline__ float bf2f(bf16_t b) { return __uint_as_float((unsigned)b << 16); }
; __device__ __forceinline__ unsigned cvt_pk_bf16(float lo, float hi) { unsigned r; asm volatile("v_cvt_pk_bf16_f32 %0, %1, %2" : "=v"(r) : "v"(lo), "v"(hi)); return r; }
; __device__ __forceinline__ float gelu_tanh(float x) { const float y = 0.7978845608028654f * (x + 0.044715f * x * x * x); const float e = __expf(2.f * y); return 0.5f * x * (2.f - 2.f * __builtin_amdgcn_rcpf(1.f + e)); }
; __device__ __forceinline__ void lru_chain(unsigned char* ws_, const float* const* in_, int l_, LAS unsigned char* lds, int tid, int bid, int G) {
;     ...
;             for (int i = 0; i < 16; i += 2) { hh = av[i] * hh + bv[i]; const float h0 = hh; hh = av[i + 1] * hh + bv[i + 1]; const int tl = 16 * w + i;
;                 const float g0 = gelu_tanh(bf2f(*(const LAS bf16_t*)(GT + tl * 144 + lane * 2))), g1 = gelu_tanh(bf2f(*(const LAS bf16_t*)(GT + (tl + 1) * 144 + lane * 2)));
;                 const unsigned pk = cvt_pk_bf16(g0 * h0, g1 * hh);
;                 *(LAS bf16_t*)(OT + tl * 144 + lane * 2) = (bf16_t)(pk & 0xffffu); *(LAS bf16_t*)(OT + (tl + 1) * 144 + lane * 2) = (bf16_t)(pk >> 16); }
;             if (w == 7) CAR[((chunk + 1) & 1) * 64 + lane] = hh;
	v_pk_mul_f32 v[242:243], v[242:243], s[20:21] op_sel_hi:[1,0]
	v_pk_mul_f32 v[244:245], v[244:245], s[20:21] op_sel_hi:[1,0]
	v_pk_mul_f32 v[246:247], v[246:247], s[20:21] op_sel_hi:[1,0]
	v_pk_mul_f32 v[248:249], v[248:249], s[20:21] op_sel_hi:[1,0]
	v_fmac_f32_e32 v72, v78, v77
	v_fmac_f32_e32 v73, v79, v72
	v_exp_f32_e32 v234, v234
	v_exp_f32_e32 v235, v235
	v_exp_f32_e32 v236, v236
	v_exp_f32_e32 v237, v237
	v_exp_f32_e32 v238, v238
	v_exp_f32_e32 v239, v239
	v_exp_f32_e32 v240, v240
	v_exp_f32_e32 v241, v241
	v_exp_f32_e32 v242, v242
	v_exp_f32_e32 v243, v243
	v_exp_f32_e32 v244, v244
	v_exp_f32_e32 v245, v245
	v_exp_f32_e32 v246, v246
	v_exp_f32_e32 v247, v247
	v_exp_f32_e32 v248, v248
	v_exp_f32_e32 v249, v249
	v_fmac_f32_e32 v2, v74, v73
	v_fmac_f32_e32 v3, v75, v2
	v_pk_mul_f32 v[216:217], v[216:217], s[22:23] op_sel_hi:[1,0]
	v_pk_mul_f32 v[218:219], v[218:219], s[22:23] op_sel_hi:[1,0]
	v_pk_mul_f32 v[220:221], v[220:221], s[22:23] op_sel_hi:[1,0]
	v_pk_mul_f32 v[222:223], v[222:223], s[22:23] op_sel_hi:[1,0]
	v_pk_mul_f32 v[224:225], v[224:225], s[22:23] op_sel_hi:[1,0]
	v_pk_mul_f32 v[226:227], v[226:227], s[22:23] op_sel_hi:[1,0]
	v_pk_mul_f32 v[228:229], v[228:229], s[22:23] op_sel_hi:[1,0]
	v_pk_mul_f32 v[230:231], v[230:231], s[22:23] op_sel_hi:[1,0]
	v_pk_add_f32 v[234:235], v[234:235], s[6:7] op_sel_hi:[1,0]
	v_pk_add_f32 v[236:237], v[236:237], s[6:7] op_sel_hi:[1,0]
	v_pk_add_f32 v[238:239], v[238:239], s[6:7] op_sel_hi:[1,0]
	v_pk_add_f32 v[240:241], v[240:241], s[6:7] op_sel_hi:[1,0]
	v_pk_add_f32 v[242:243], v[242:243], s[6:7] op_sel_hi:[1,0]
	v_pk_add_f32 v[244:245], v[244:245], s[6:7] op_sel_hi:[1,0]
	v_pk_add_f32 v[246:247], v[246:247], s[6:7] op_sel_hi:[1,0]
	v_pk_add_f32 v[248:249], v[248:249], s[6:7] op_sel_hi:[1,0]
	v_rcp_f32_e32 v234, v234
	v_rcp_f32_e32 v235, v235
	v_rcp_f32_e32 v236, v236
	v_rcp_f32_e32 v237, v237
	v_rcp_f32_e32 v238, v238
	v_rcp_f32_e32 v239, v239
	v_rcp_f32_e32 v240, v240
	v_rcp_f32_e32 v241, v241
	v_rcp_f32_e32 v242, v242
	v_rcp_f32_e32 v243, v243
	v_rcp_f32_e32 v244, v244
	v_rcp_f32_e32 v245, v245
	v_rcp_f32_e32 v246, v246
	v_rcp_f32_e32 v247, v247
	v_rcp_f32_e32 v248, v248
	v_rcp_f32_e32 v249, v249
	v_fma_f32 v234, v234, -2.0, 2.0
	v_fma_f32 v235, v235, -2.0, 2.0
	v_fma_f32 v236, v236, -2.0, 2.0
	v_fma_f32 v237, v237, -2.0, 2.0
	v_fma_f32 v238, v238, -2.0, 2.0
	v_fma_f32 v239, v239, -2.0, 2.0
	v_fma_f32 v240, v240, -2.0, 2.0
	v_fma_f32 v241, v241, -2.0, 2.0
	v_fma_f32 v242, v242, -2.0, 2.0
	v_fma_f32 v243, v243, -2.0, 2.0
	v_fma_f32 v244, v244, -2.0, 2.0
	v_fma_f32 v245, v245, -2.0, 2.0
	v_fma_f32 v246, v246, -2.0, 2.0
	v_fma_f32 v247, v247, -2.0, 2.0
	v_fma_f32 v248, v248, -2.0, 2.0
	v_fma_f32 v249, v249, -2.0, 2.0
	v_pk_mul_f32 v[216:217], v[216:217], v[234:235]
	v_pk_mul_f32 v[218:219], v[218:219], v[236:237]
	v_pk_mul_f32 v[220:221], v[220:221], v[238:239]
	v_pk_mul_f32 v[222:223], v[222:223], v[240:241]
	v_pk_mul_f32 v[224:225], v[224:225], v[242:243]
	v_pk_mul_f32 v[226:227], v[226:227], v[244:245]
	v_pk_mul_f32 v[228:229], v[228:229], v[246:247]
	v_pk_mul_f32 v[230:231], v[230:231], v[248:249]
	v_pk_mul_f32 v[234:235], v[96:97], v[216:217]
	v_pk_mul_f32 v[236:237], v[92:93], v[218:219]
	v_pk_mul_f32 v[238:239], v[88:89], v[220:221]
	v_pk_mul_f32 v[240:241], v[84:85], v[222:223]
	v_pk_mul_f32 v[242:243], v[80:81], v[224:225]
	v_pk_mul_f32 v[244:245], v[76:77], v[226:227]
	v_pk_mul_f32 v[246:247], v[72:73], v[228:229]
	v_pk_mul_f32 v[248:249], v[2:3], v[230:231]
	v_cvt_pk_bf16_f32 v216, v234, v235
	v_cvt_pk_bf16_f32 v217, v236, v237
	v_cvt_pk_bf16_f32 v218, v238, v239
	v_cvt_pk_bf16_f32 v219, v240, v241
	v_cvt_pk_bf16_f32 v220, v242, v243
	v_cvt_pk_bf16_f32 v221, v244, v245
	v_cvt_pk_bf16_f32 v222, v246, v247
	v_cvt_pk_bf16_f32 v223, v248, v249
	ds_write_b16 v205, v216 offset:18432
	ds_write_b16_d16_hi v205, v216 offset:18576
	ds_write_b16 v205, v217 offset:18720
	ds_write_b16_d16_hi v205, v217 offset:18864
	ds_write_b16 v205, v218 offset:19008
	ds_write_b16_d16_hi v205, v218 offset:19152
	ds_write_b16 v205, v219 offset:19296
	ds_write_b16_d16_hi v205, v219 offset:19440
	ds_write_b16 v205, v220 offset:19584
	ds_write_b16_d16_hi v205, v220 offset:19728
	ds_write_b16 v205, v221 offset:19872
	ds_write_b16_d16_hi v205, v221 offset:20016
	ds_write_b16 v205, v222 offset:20160
	ds_write_b16_d16_hi v205, v222 offset:20304
	ds_write_b16 v205, v223 offset:20448
	ds_write_b16_d16_hi v205, v223 offset:20592
	s_cbranch_vccz .LBB0_186
	v_bitop3_b32 v1, s2, 64, v151 bitop3:0x36
	v_lshl_add_u32 v1, v1, 2, 0
	v_add_u32_e32 v1, 0x1fb00, v1
	ds_write_b32 v1, v3
	s_branch .LBB0_186
